# attention queues: on a drained queue read all eight counters at once and skip the empty ones (one round trip instead of eight dependent atomics)
# speedup vs baseline: 1.0019x; 1.0019x over previous
; #define LAS __attribute__((address_space(3)))
; __device__ __forceinline__ void phase_attn(const Params& p, LAS unsigned char* lds) {
;     ...
;         if (tid == 0) { unsigned v = 0xffffffffu;
;             while (qoff < 8) { const int qx = (myx + qoff) & 7; const unsigned n = atomicAdd(ctr + 64 * qx, 1u); if (n < 64u) { v = (unsigned)((qx + 8 * (n >> 4)) * 16 + (n & 15)); break; } ++qoff; }
;             *(LAS unsigned*)(lds + A_ITEM) = v; }
.Latt_claim:
	v_cmp_gt_i32_e32 vcc, 8, v133
	s_cbranch_vccz .Latt_claimed
	v_add_u32_e32 v1, s43, v133
	v_and_b32_e32 v1, 7, v1
	v_lshlrev_b32_e32 v2, 8, v1
	global_atomic_add v240, v2, v131, s[26:27] sc0
	s_waitcnt vmcnt(0)
	v_cmp_gt_u32_e32 vcc, 64, v240
	s_cbranch_vccnz .Latt_got
	s_add_i32 s96, s43, 0
	s_and_b32 s96, s96, 7
	s_lshl_b32 s96, s96, 8
	v_mov_b32_e32 v2, s96
	global_load_dword v171, v2, s[26:27] sc1
	s_add_i32 s96, s43, 1
	s_and_b32 s96, s96, 7
	s_lshl_b32 s96, s96, 8
	v_mov_b32_e32 v2, s96
	global_load_dword v172, v2, s[26:27] sc1
	s_add_i32 s96, s43, 2
	s_and_b32 s96, s96, 7
	s_lshl_b32 s96, s96, 8
	v_mov_b32_e32 v2, s96
	global_load_dword v173, v2, s[26:27] sc1
	s_add_i32 s96, s43, 3
	s_and_b32 s96, s96, 7
	s_lshl_b32 s96, s96, 8
	v_mov_b32_e32 v2, s96
	global_load_dword v174, v2, s[26:27] sc1
	s_add_i32 s96, s43, 4
	s_and_b32 s96, s96, 7
	s_lshl_b32 s96, s96, 8
	v_mov_b32_e32 v2, s96
	global_load_dword v175, v2, s[26:27] sc1
	s_add_i32 s96, s43, 5
	s_and_b32 s96, s96, 7
	s_lshl_b32 s96, s96, 8
	v_mov_b32_e32 v2, s96
	global_load_dword v176, v2, s[26:27] sc1
	s_add_i32 s96, s43, 6
	s_and_b32 s96, s96, 7
	s_lshl_b32 s96, s96, 8
	v_mov_b32_e32 v2, s96
	global_load_dword v177, v2, s[26:27] sc1
	s_add_i32 s96, s43, 7
	s_and_b32 s96, s96, 7
	s_lshl_b32 s96, s96, 8
	v_mov_b32_e32 v2, s96
	global_load_dword v178, v2, s[26:27] sc1
	s_waitcnt vmcnt(0)
	s_mov_b32 s97, 0
	v_cmp_le_u32_e32 vcc, 64, v171
	s_and_b32 s96, vcc_lo, 1
	s_or_b32 s97, s97, s96
	v_cmp_le_u32_e32 vcc, 64, v172
	s_and_b32 s96, vcc_lo, 1
	s_lshl_b32 s96, s96, 1
	s_or_b32 s97, s97, s96
	v_cmp_le_u32_e32 vcc, 64, v173
	s_and_b32 s96, vcc_lo, 1
	s_lshl_b32 s96, s96, 2
	s_or_b32 s97, s97, s96
	v_cmp_le_u32_e32 vcc, 64, v174
	s_and_b32 s96, vcc_lo, 1
	s_lshl_b32 s96, s96, 3
	s_or_b32 s97, s97, s96
	v_cmp_le_u32_e32 vcc, 64, v175
	s_and_b32 s96, vcc_lo, 1
	s_lshl_b32 s96, s96, 4
	s_or_b32 s97, s97, s96
	v_cmp_le_u32_e32 vcc, 64, v176
	s_and_b32 s96, vcc_lo, 1
	s_lshl_b32 s96, s96, 5
	s_or_b32 s97, s97, s96
	v_cmp_le_u32_e32 vcc, 64, v177
	s_and_b32 s96, vcc_lo, 1
	s_lshl_b32 s96, s96, 6
	s_or_b32 s97, s97, s96
	v_cmp_le_u32_e32 vcc, 64, v178
	s_and_b32 s96, vcc_lo, 1
	s_lshl_b32 s96, s96, 7
	s_or_b32 s97, s97, s96
	v_readfirstlane_b32 s98, v133
	s_add_i32 s98, s98, 1
.Latt_qskip:
	s_cmp_ge_u32 s98, 8
	s_cbranch_scc1 .Latt_qdone
	s_lshr_b32 s99, s97, s98
	s_bitcmp1_b32 s99, 0
	s_cbranch_scc0 .Latt_qdone
	s_add_i32 s98, s98, 1
	s_branch .Latt_qskip
.Latt_qdone:
	v_mov_b32_e32 v133, s98
	s_branch .Latt_claim
.Latt_got:
	v_lshrrev_b32_e32 v0, 1, v240
	v_and_or_b32 v0, v0, 24, v1
	v_and_b32_e32 v2, 15, v240
	v_lshl_or_b32 v0, v0, 4, v2
